# attention tile loop: rescale-needed test kept as a scalar flag (compare only in the new-maximum path), tile-Y row-max chain writes its copy register directly, post-asm pads dropped
# speedup vs baseline: 1.0293x; 1.0041x over previous
.LBB0_423:
	s_lshl_b32 s16, s19, 14
	s_add_i32 s4, s16, 16
	v_add_u32_e32 v96, s4, v185
	ds_read_b128 v[198:201], v96 offset:49152
	ds_read_b128 v[202:205], v96 offset:57344
	v_xor_b32_e32 v80, 0x80000000, v195
	v_mov_b32_e32 v81, v80
	v_mov_b64_e32 v[82:83], v[80:81]
	v_mov_b64_e32 v[84:85], v[80:81]
	v_mov_b64_e32 v[86:87], v[80:81]
	v_mov_b64_e32 v[88:89], v[80:81]
	v_mov_b64_e32 v[90:91], v[80:81]
	v_mov_b64_e32 v[92:93], v[80:81]
	v_mov_b64_e32 v[94:95], v[80:81]
	v_exp_f32_e32 v221, v64
	s_waitcnt lgkmcnt(1)
	v_mfma_f32_32x32x16_bf16 v[96:111], v[198:201], v[124:127], v[80:95]
	v_add_f32_e32 v64, v153, v152
	v_add_f32_e32 v64, v154, v64
	v_add_u32_e32 v197, s4, v189
	v_add_f32_e32 v64, v155, v64
	v_add_f32_e32 v64, v156, v64
	v_add_f32_e32 v64, v157, v64
	v_add_f32_e32 v64, v158, v64
	s_waitcnt lgkmcnt(0)
	v_mfma_f32_32x32x16_bf16 v[80:95], v[202:205], v[124:127], v[80:95]
	ds_read_b128 v[198:201], v197 offset:49152
	ds_read_b128 v[202:205], v197 offset:57344
	v_add_f32_e32 v64, v159, v64
	v_add_f32_e32 v64, v144, v64
	v_add_f32_e32 v64, v145, v64
	v_add_f32_e32 v64, v146, v64
	v_add_u32_e32 v197, s4, v192
	v_add_f32_e32 v64, v147, v64
	s_waitcnt lgkmcnt(1)
	v_mfma_f32_32x32x16_bf16 v[96:111], v[198:201], v[120:123], v[96:111]
	ds_read_b128 v[198:201], v197 offset:49152
	ds_read_b128 v[206:209], v197 offset:57344
	v_add_f32_e32 v64, v148, v64
	v_exp_f32_e32 v222, v65
	v_add_f32_e32 v64, v149, v64
	v_exp_f32_e32 v223, v66
	v_add_f32_e32 v64, v150, v64
	v_exp_f32_e32 v224, v67
	s_waitcnt lgkmcnt(2)
	v_mfma_f32_32x32x16_bf16 v[80:95], v[202:205], v[120:123], v[80:95]
	v_add_f32_e32 v64, v151, v64
	v_add_f32_e32 v64, v221, v64
	v_add_f32_e32 v64, v222, v64
	v_add_f32_e32 v64, v223, v64
	v_exp_f32_e32 v71, v71
	v_add_f32_e32 v64, v224, v64
	v_add_u32_e32 v197, s4, v194
	s_waitcnt lgkmcnt(1)
	v_mfma_f32_32x32x16_bf16 v[96:111], v[198:201], v[116:119], v[96:111]
	v_exp_f32_e32 v199, v68
	v_exp_f32_e32 v200, v69
	v_exp_f32_e32 v201, v70
	v_exp_f32_e32 v225, v72
	v_add_f32_e32 v64, v199, v64
	ds_read_b128 v[202:205], v197 offset:49152
	ds_read_b128 v[210:213], v197 offset:57344
	v_exp_f32_e32 v226, v73
	s_waitcnt lgkmcnt(2)
	v_mfma_f32_32x32x16_bf16 v[80:95], v[206:209], v[116:119], v[80:95]
	v_add_f32_e32 v64, v200, v64
	v_exp_f32_e32 v227, v74
	v_add_f32_e32 v64, v201, v64
	v_exp_f32_e32 v206, v75
	v_add_f32_e32 v64, v71, v64
	v_exp_f32_e32 v207, v76
	v_add_f32_e32 v64, v225, v64
	v_exp_f32_e32 v208, v77
	v_add_f32_e32 v64, v226, v64
	v_exp_f32_e32 v209, v78
	s_waitcnt lgkmcnt(1)
	v_mfma_f32_32x32x16_bf16 v[96:111], v[202:205], v[112:115], v[96:111]
	v_add_f32_e32 v64, v227, v64
	v_exp_f32_e32 v79, v79
	v_add_f32_e32 v64, v206, v64
	v_add_f32_e32 v64, v207, v64
	v_add_f32_e32 v64, v208, v64
	v_add_f32_e32 v64, v209, v64
	v_add_f32_e32 v197, v79, v64
	s_waitcnt lgkmcnt(0)
	v_mfma_f32_32x32x16_bf16 v[80:95], v[210:213], v[112:115], v[80:95]
	v_cvt_pk_bf16_f32 v64, v152, v153
	v_cvt_pk_bf16_f32 v65, v154, v155
	v_cvt_pk_bf16_f32 v66, v156, v157
	v_cvt_pk_bf16_f32 v67, v158, v159
	v_cvt_pk_bf16_f32 v72, v144, v145
	v_cvt_pk_bf16_f32 v73, v146, v147
	v_cvt_pk_bf16_f32 v74, v148, v149
	v_cvt_pk_bf16_f32 v75, v150, v151
	v_cvt_pk_bf16_f32 v68, v221, v222
	v_cvt_pk_bf16_f32 v69, v223, v224
	v_cvt_pk_bf16_f32 v70, v199, v200
	v_cvt_pk_bf16_f32 v71, v201, v71
	v_cvt_pk_bf16_f32 v76, v225, v226
	v_cvt_pk_bf16_f32 v77, v227, v206
	v_cvt_pk_bf16_f32 v78, v207, v208
	v_cvt_pk_bf16_f32 v79, v209, v79
	global_load_dwordx4 v[144:147], v244, s[98:99]
	global_load_dwordx4 v[148:151], v245, s[98:99]
	global_load_dwordx4 v[152:155], v242, s[98:99]
	global_load_dwordx4 v[156:159], v243, s[98:99]
	s_add_u32 s98, s98, 0x10000
	s_addc_u32 s99, s99, 0
	v_lshl_add_u32 v199, s18, 14, v181
	ds_read_b64_tr_b16 v[200:201], v199 offset:0
	ds_read_b64_tr_b16 v[202:203], v199 offset:0x100
	ds_read_b64_tr_b16 v[204:205], v199 offset:0x1000
	ds_read_b64_tr_b16 v[206:207], v199 offset:0x1100
	ds_read_b64_tr_b16 v[208:209], v199 offset:0x2000
	ds_read_b64_tr_b16 v[210:211], v199 offset:0x2100
	ds_read_b64_tr_b16 v[222:223], v199 offset:0x3000
	ds_read_b64_tr_b16 v[224:225], v199 offset:0x3100
	s_waitcnt lgkmcnt(6)
	v_mfma_f32_32x32x16_bf16 v[0:15], v[64:67], v[200:203], v[0:15]
	v_max_f32_e32 v200, v96, v97
	v_max3_f32 v200, v200, v98, v99
	v_max3_f32 v200, v200, v100, v101
	v_max3_f32 v200, v200, v102, v103
	v_max3_f32 v200, v200, v104, v105
	s_waitcnt lgkmcnt(4)
	v_mfma_f32_32x32x16_bf16 v[0:15], v[72:75], v[204:207], v[0:15]
	v_max3_f32 v200, v200, v106, v107
	v_max3_f32 v202, v200, v108, v109
	ds_read_b64_tr_b16 v[200:201], v199 offset:0x200
	v_max3_f32 v212, v202, v110, v111
	ds_read_b64_tr_b16 v[202:203], v199 offset:0x300
	ds_read_b64_tr_b16 v[204:205], v199 offset:0x1200
	ds_read_b64_tr_b16 v[206:207], v199 offset:0x1300
	s_waitcnt lgkmcnt(6)
	v_mfma_f32_32x32x16_bf16 v[0:15], v[68:71], v[208:211], v[0:15]
	ds_read_b64_tr_b16 v[208:209], v199 offset:0x2200
	ds_read_b64_tr_b16 v[210:211], v199 offset:0x2300
	ds_read_b64_tr_b16 v[226:227], v199 offset:0x3200
	ds_read_b64_tr_b16 v[228:229], v199 offset:0x3300
	s_waitcnt lgkmcnt(8)
	v_mfma_f32_32x32x16_bf16 v[0:15], v[76:79], v[222:225], v[0:15]
	s_waitcnt lgkmcnt(6)
	v_mfma_f32_32x32x16_bf16 v[48:63], v[64:67], v[200:203], v[48:63]
	v_max3_f32 v212, v212, v80, v81
	v_max3_f32 v200, v212, v82, v83
	ds_read_b64_tr_b16 v[202:203], v199 offset:0x400
	v_max3_f32 v200, v200, v84, v85
	v_max3_f32 v200, v200, v86, v87
	v_max3_f32 v200, v200, v88, v89
	v_max3_f32 v200, v200, v90, v91
	s_waitcnt lgkmcnt(5)
	v_mfma_f32_32x32x16_bf16 v[48:63], v[72:75], v[204:207], v[48:63]
	ds_read_b64_tr_b16 v[204:205], v199 offset:0x500
	ds_read_b64_tr_b16 v[206:207], v199 offset:0x1400
	v_max3_f32 v200, v200, v92, v93
	v_max3_f32 v200, v200, v94, v95
	s_waitcnt lgkmcnt(5)
	v_mfma_f32_32x32x16_bf16 v[48:63], v[68:71], v[208:211], v[48:63]
	ds_read_b64_tr_b16 v[208:209], v199 offset:0x1500
	ds_read_b64_tr_b16 v[210:211], v199 offset:0x2400
	ds_read_b64_tr_b16 v[212:213], v199 offset:0x2500
	ds_read_b64_tr_b16 v[222:223], v199 offset:0x3400
	ds_read_b64_tr_b16 v[224:225], v199 offset:0x3500
	s_waitcnt lgkmcnt(8)
	v_mfma_f32_32x32x16_bf16 v[48:63], v[76:79], v[226:229], v[48:63]
	s_waitcnt lgkmcnt(6)
	v_mfma_f32_32x32x16_bf16 v[32:47], v[64:67], v[202:205], v[32:47]
	v_cmp_ge_f32_e32 vcc, s63, v200
	s_cmp_eq_u64 vcc, exec
	s_waitcnt lgkmcnt(4)
	v_mfma_f32_32x32x16_bf16 v[32:47], v[72:75], v[206:209], v[32:47]
	s_waitcnt lgkmcnt(2)
	v_mfma_f32_32x32x16_bf16 v[32:47], v[68:71], v[210:213], v[32:47]
	s_waitcnt lgkmcnt(0)
	v_mfma_f32_32x32x16_bf16 v[32:47], v[76:79], v[222:225], v[32:47]
	s_cbranch_scc0 .LBB0_438
	v_mov_b32_e32 v200, 1.0
	s_mov_b64 s[100:101], 0
.LBB0_425:
	ds_read_b64_tr_b16 v[202:203], v199 offset:0x600
	ds_read_b64_tr_b16 v[204:205], v199 offset:0x700
	ds_read_b64_tr_b16 v[206:207], v199 offset:0x1600
	ds_read_b64_tr_b16 v[208:209], v199 offset:0x1700
	ds_read_b64_tr_b16 v[210:211], v199 offset:0x2600
	ds_read_b64_tr_b16 v[212:213], v199 offset:0x2700
	ds_read_b64_tr_b16 v[222:223], v199 offset:0x3600
	ds_read_b64_tr_b16 v[224:225], v199 offset:0x3700
	s_add_i32 s4, s19, 1
	s_cmp_lg_u32 s19, 2
	s_cselect_b32 s18, s4, 0
	s_waitcnt lgkmcnt(6)
	v_mfma_f32_32x32x16_bf16 v[16:31], v[64:67], v[202:205], v[16:31]
	s_lshl_b32 s4, s18, 14
	s_add_i32 s17, s4, 16
	v_add_u32_e32 v64, s17, v184
	s_waitcnt vmcnt(4)
	s_waitcnt vmcnt(4)
	ds_write_b128 v64, v[132:135]
	v_add_u32_e32 v64, s17, v186
	ds_write_b128 v64, v[140:143]
	s_waitcnt lgkmcnt(6)
	v_mfma_f32_32x32x16_bf16 v[16:31], v[72:75], v[206:209], v[16:31]
	v_add_u32_e32 v64, s17, v183
	ds_write_b128 v64, v[128:131] offset:49152
	v_add_u32_e32 v64, s17, v188
	s_mov_b64 vcc, s[100:101]
	ds_write_b128 v64, v[136:139] offset:49152
	s_waitcnt lgkmcnt(6)
	v_mfma_f32_32x32x16_bf16 v[16:31], v[68:71], v[210:213], v[16:31]
	s_waitcnt lgkmcnt(4)
	v_mfma_f32_32x32x16_bf16 v[16:31], v[76:79], v[222:225], v[16:31]
	s_cbranch_vccz .LBB0_429
	s_and_saveexec_b64 s[4:5], s[0:1]
	ds_write_b32 v179, v200 offset:128
	s_or_b64 exec, exec, s[4:5]
	s_waitcnt lgkmcnt(0)
	v_add_u32_e32 v76, v177, v176
	ds_read_b128 v[64:67], v76 offset:224
	ds_read_b128 v[68:71], v76 offset:192
	ds_read_b128 v[72:75], v76 offset:160
	ds_read_b128 v[76:79], v76 offset:128
	s_waitcnt lgkmcnt(3)
	v_pk_mul_f32 v[12:13], v[12:13], v[64:65]
	s_waitcnt lgkmcnt(2)
	v_pk_mul_f32 v[8:9], v[8:9], v[68:69]
	s_waitcnt lgkmcnt(1)
	v_pk_mul_f32 v[4:5], v[4:5], v[72:73]
	v_pk_mul_f32 v[14:15], v[14:15], v[66:67]
	v_pk_mul_f32 v[10:11], v[10:11], v[70:71]
	v_pk_mul_f32 v[6:7], v[6:7], v[74:75]
	s_waitcnt lgkmcnt(0)
	v_pk_mul_f32 v[2:3], v[2:3], v[78:79]
	v_pk_mul_f32 v[0:1], v[0:1], v[76:77]
	v_pk_mul_f32 v[60:61], v[60:61], v[64:65]
	v_pk_mul_f32 v[56:57], v[56:57], v[68:69]
	v_pk_mul_f32 v[52:53], v[52:53], v[72:73]
	v_pk_mul_f32 v[62:63], v[62:63], v[66:67]
	v_pk_mul_f32 v[58:59], v[58:59], v[70:71]
	v_pk_mul_f32 v[54:55], v[54:55], v[74:75]
	v_pk_mul_f32 v[50:51], v[50:51], v[78:79]
	v_pk_mul_f32 v[48:49], v[48:49], v[76:77]
	v_pk_mul_f32 v[44:45], v[44:45], v[64:65]
	v_pk_mul_f32 v[40:41], v[40:41], v[68:69]
	v_pk_mul_f32 v[36:37], v[36:37], v[72:73]
	v_pk_mul_f32 v[46:47], v[46:47], v[66:67]
	v_pk_mul_f32 v[42:43], v[42:43], v[70:71]
	v_pk_mul_f32 v[38:39], v[38:39], v[74:75]
	v_pk_mul_f32 v[34:35], v[34:35], v[78:79]
	v_pk_mul_f32 v[32:33], v[32:33], v[76:77]
	v_pk_mul_f32 v[28:29], v[28:29], v[64:65]
	v_pk_mul_f32 v[24:25], v[24:25], v[68:69]
	v_pk_mul_f32 v[20:21], v[20:21], v[72:73]
	v_pk_mul_f32 v[30:31], v[30:31], v[66:67]
	v_pk_mul_f32 v[26:27], v[26:27], v[70:71]
	v_pk_mul_f32 v[22:23], v[22:23], v[74:75]
	v_pk_mul_f32 v[18:19], v[18:19], v[78:79]
	v_pk_mul_f32 v[16:17], v[16:17], v[76:77]

.LBB0_431:
	v_add_u32_e32 v203, s16, v181
	ds_read_b64_tr_b16 v[204:205], v203 offset:0
	ds_read_b64_tr_b16 v[206:207], v203 offset:0x100
	ds_read_b64_tr_b16 v[208:209], v203 offset:0x1000
	ds_read_b64_tr_b16 v[210:211], v203 offset:0x1100
	ds_read_b64_tr_b16 v[222:223], v203 offset:0x2000
	ds_read_b64_tr_b16 v[224:225], v203 offset:0x2100
	ds_read_b64_tr_b16 v[226:227], v203 offset:0x3000
	ds_read_b64_tr_b16 v[228:229], v203 offset:0x3100
	s_waitcnt lgkmcnt(0)
	v_mfma_f32_32x32x16_bf16 v[0:15], v[88:91], v[204:207], v[0:15]
	v_max_f32_e32 v199, v96, v97
	ds_read_b64_tr_b16 v[204:205], v203 offset:0x200
	ds_read_b64_tr_b16 v[206:207], v203 offset:0x300
	v_max3_f32 v199, v199, v98, v99
	v_max3_f32 v199, v199, v100, v101
	v_mfma_f32_32x32x16_bf16 v[0:15], v[92:95], v[208:211], v[0:15]
	ds_read_b64_tr_b16 v[208:209], v203 offset:0x1200
	ds_read_b64_tr_b16 v[210:211], v203 offset:0x1300
	v_max3_f32 v199, v199, v102, v103
	v_max3_f32 v199, v199, v104, v105
	v_max3_f32 v199, v199, v106, v107
	v_max3_f32 v199, v199, v108, v109
	v_max3_f32 v199, v199, v110, v111
	v_mfma_f32_32x32x16_bf16 v[0:15], v[80:83], v[222:225], v[0:15]
	ds_read_b64_tr_b16 v[222:223], v203 offset:0x2200
	ds_read_b64_tr_b16 v[224:225], v203 offset:0x2300
	ds_read_b64_tr_b16 v[230:231], v203 offset:0x3200
	ds_read_b64_tr_b16 v[232:233], v203 offset:0x3300
	v_mfma_f32_32x32x16_bf16 v[0:15], v[84:87], v[226:229], v[0:15]
	s_waitcnt lgkmcnt(6)
	v_mfma_f32_32x32x16_bf16 v[48:63], v[88:91], v[204:207], v[48:63]
	v_max3_f32 v199, v199, v64, v65
	v_max3_f32 v199, v199, v66, v67
	ds_read_b64_tr_b16 v[206:207], v203 offset:0x400
	v_max3_f32 v199, v199, v68, v69
	v_max3_f32 v199, v199, v70, v71
	v_max3_f32 v199, v199, v72, v73
	v_max3_f32 v199, v199, v74, v75
	s_waitcnt lgkmcnt(5)
	v_mfma_f32_32x32x16_bf16 v[48:63], v[92:95], v[208:211], v[48:63]
	ds_read_b64_tr_b16 v[208:209], v203 offset:0x500
	ds_read_b64_tr_b16 v[210:211], v203 offset:0x1400
	ds_read_b64_tr_b16 v[212:213], v203 offset:0x1500
	v_max3_f32 v199, v199, v76, v77
	v_max3_f32 v204, v199, v78, v79
	s_waitcnt lgkmcnt(6)
	v_mfma_f32_32x32x16_bf16 v[48:63], v[80:83], v[222:225], v[48:63]
	ds_read_b64_tr_b16 v[222:223], v203 offset:0x2400
	ds_read_b64_tr_b16 v[224:225], v203 offset:0x2500
	ds_read_b64_tr_b16 v[226:227], v203 offset:0x3400
	ds_read_b64_tr_b16 v[228:229], v203 offset:0x3500
	s_waitcnt lgkmcnt(8)
	v_mfma_f32_32x32x16_bf16 v[48:63], v[84:87], v[230:233], v[48:63]
	s_waitcnt lgkmcnt(6)
	v_mfma_f32_32x32x16_bf16 v[32:47], v[88:91], v[206:209], v[32:47]
	v_cmp_ge_f32_e32 vcc, s63, v204
	s_cmp_eq_u64 vcc, exec
	v_mov_b32_e32 v199, 1.0
	s_mov_b64 s[100:101], 0
	s_waitcnt lgkmcnt(4)
	v_mfma_f32_32x32x16_bf16 v[32:47], v[92:95], v[210:213], v[32:47]
	s_waitcnt lgkmcnt(2)
	v_mfma_f32_32x32x16_bf16 v[32:47], v[80:83], v[222:225], v[32:47]
	s_waitcnt lgkmcnt(0)
	v_mfma_f32_32x32x16_bf16 v[32:47], v[84:87], v[226:229], v[32:47]
	s_cbranch_scc0 .LBB0_439
.LBB0_432:
	ds_read_b64_tr_b16 v[204:205], v203 offset:0x600
	ds_read_b64_tr_b16 v[206:207], v203 offset:0x700
	ds_read_b64_tr_b16 v[208:209], v203 offset:0x1600
	ds_read_b64_tr_b16 v[210:211], v203 offset:0x1700
	ds_read_b64_tr_b16 v[222:223], v203 offset:0x2600
	ds_read_b64_tr_b16 v[224:225], v203 offset:0x2700
	ds_read_b64_tr_b16 v[226:227], v203 offset:0x3600
	ds_read_b64_tr_b16 v[228:229], v203 offset:0x3700
	s_add_i32 s16, s18, 1
	s_cmp_lg_u32 s18, 2
	s_cselect_b32 s19, s16, 0
	s_waitcnt lgkmcnt(6)
	v_mfma_f32_32x32x16_bf16 v[16:31], v[88:91], v[204:207], v[16:31]
	s_lshl_b32 s16, s19, 14
	s_add_i32 s16, s16, 16
	s_waitcnt vmcnt(4)
	v_add_u32_e32 v88, s16, v184
	ds_write_b128 v88, v[144:147]
	s_mov_b64 vcc, s[100:101]
	s_waitcnt lgkmcnt(5)
	v_mfma_f32_32x32x16_bf16 v[16:31], v[92:95], v[208:211], v[16:31]
	s_waitcnt lgkmcnt(3)
	v_mfma_f32_32x32x16_bf16 v[16:31], v[80:83], v[222:225], v[16:31]
	v_add_u32_e32 v80, s16, v186
	ds_write_b128 v80, v[148:151]
	v_add_u32_e32 v80, s16, v183
	ds_write_b128 v80, v[152:155] offset:49152
	v_add_u32_e32 v80, s16, v188
	ds_write_b128 v80, v[156:159] offset:49152
	s_waitcnt lgkmcnt(4)
	v_mfma_f32_32x32x16_bf16 v[16:31], v[84:87], v[226:229], v[16:31]
	s_cbranch_vccz .LBB0_436
	s_and_saveexec_b64 s[16:17], s[0:1]
	ds_write_b32 v179, v199 offset:128
	s_or_b64 exec, exec, s[16:17]
	s_waitcnt lgkmcnt(0)
	v_add_u32_e32 v92, v177, v176
	ds_read_b128 v[80:83], v92 offset:224
	ds_read_b128 v[84:87], v92 offset:192
	ds_read_b128 v[88:91], v92 offset:160
	ds_read_b128 v[92:95], v92 offset:128
	s_waitcnt lgkmcnt(3)
	v_pk_mul_f32 v[12:13], v[12:13], v[80:81]
	s_waitcnt lgkmcnt(2)
	v_pk_mul_f32 v[8:9], v[8:9], v[84:85]
	s_waitcnt lgkmcnt(1)
	v_pk_mul_f32 v[4:5], v[4:5], v[88:89]
	v_pk_mul_f32 v[14:15], v[14:15], v[82:83]
	v_pk_mul_f32 v[10:11], v[10:11], v[86:87]
	v_pk_mul_f32 v[6:7], v[6:7], v[90:91]
	s_waitcnt lgkmcnt(0)
	v_pk_mul_f32 v[2:3], v[2:3], v[94:95]
	v_pk_mul_f32 v[0:1], v[0:1], v[92:93]
	v_pk_mul_f32 v[60:61], v[60:61], v[80:81]
	v_pk_mul_f32 v[56:57], v[56:57], v[84:85]
	v_pk_mul_f32 v[52:53], v[52:53], v[88:89]
	v_pk_mul_f32 v[62:63], v[62:63], v[82:83]
	v_pk_mul_f32 v[58:59], v[58:59], v[86:87]
	v_pk_mul_f32 v[54:55], v[54:55], v[90:91]
	v_pk_mul_f32 v[50:51], v[50:51], v[94:95]
	v_pk_mul_f32 v[48:49], v[48:49], v[92:93]
	v_pk_mul_f32 v[44:45], v[44:45], v[80:81]
	v_pk_mul_f32 v[40:41], v[40:41], v[84:85]
	v_pk_mul_f32 v[36:37], v[36:37], v[88:89]
	v_pk_mul_f32 v[46:47], v[46:47], v[82:83]
	v_pk_mul_f32 v[42:43], v[42:43], v[86:87]
	v_pk_mul_f32 v[38:39], v[38:39], v[90:91]
	v_pk_mul_f32 v[34:35], v[34:35], v[94:95]
	v_pk_mul_f32 v[32:33], v[32:33], v[92:93]
	v_pk_mul_f32 v[28:29], v[28:29], v[80:81]
	v_pk_mul_f32 v[24:25], v[24:25], v[84:85]
	v_pk_mul_f32 v[20:21], v[20:21], v[88:89]
	v_pk_mul_f32 v[30:31], v[30:31], v[82:83]
	v_pk_mul_f32 v[26:27], v[26:27], v[86:87]
	v_pk_mul_f32 v[22:23], v[22:23], v[90:91]
	v_pk_mul_f32 v[18:19], v[18:19], v[94:95]
	v_pk_mul_f32 v[16:17], v[16:17], v[92:93]

.LBB0_438:
	v_mov_b32_e32 v201, v200
	s_nop 1
	v_permlane32_swap_b32_e32 v200, v201
	v_max_f32_e32 v200, v200, v201
	v_max_f32_e32 v202, 0, v200
	v_exp_f32_e64 v200, -v202
	v_add_f32_e32 v195, v195, v202
	v_pk_add_f32 v[96:97], v[96:97], v[202:203] op_sel_hi:[1,0] neg_lo:[0,1] neg_hi:[0,1]
	v_pk_add_f32 v[98:99], v[98:99], v[202:203] op_sel_hi:[1,0] neg_lo:[0,1] neg_hi:[0,1]
	v_pk_add_f32 v[100:101], v[100:101], v[202:203] op_sel_hi:[1,0] neg_lo:[0,1] neg_hi:[0,1]
	v_pk_add_f32 v[102:103], v[102:103], v[202:203] op_sel_hi:[1,0] neg_lo:[0,1] neg_hi:[0,1]
	v_pk_add_f32 v[104:105], v[104:105], v[202:203] op_sel_hi:[1,0] neg_lo:[0,1] neg_hi:[0,1]
	v_pk_add_f32 v[106:107], v[106:107], v[202:203] op_sel_hi:[1,0] neg_lo:[0,1] neg_hi:[0,1]
	v_pk_add_f32 v[108:109], v[108:109], v[202:203] op_sel_hi:[1,0] neg_lo:[0,1] neg_hi:[0,1]
	v_pk_add_f32 v[110:111], v[110:111], v[202:203] op_sel_hi:[1,0] neg_lo:[0,1] neg_hi:[0,1]
	v_sub_f32_e32 v95, v95, v202
	v_sub_f32_e32 v94, v94, v202
	v_sub_f32_e32 v93, v93, v202
	v_sub_f32_e32 v92, v92, v202
	v_sub_f32_e32 v91, v91, v202
	v_sub_f32_e32 v90, v90, v202
	v_sub_f32_e32 v89, v89, v202
	v_sub_f32_e32 v88, v88, v202
	v_sub_f32_e32 v87, v87, v202
	v_sub_f32_e32 v86, v86, v202
	v_sub_f32_e32 v85, v85, v202
	v_sub_f32_e32 v84, v84, v202
	v_sub_f32_e32 v83, v83, v202
	v_sub_f32_e32 v82, v82, v202
	v_sub_f32_e32 v81, v81, v202
	v_sub_f32_e32 v80, v80, v202
	v_cmp_gt_f32_e64 s[100:101], 1.0, v200
	s_branch .LBB0_425
.LBB0_439:
	v_mov_b32_e32 v199, v204
	s_nop 1
	v_permlane32_swap_b32_e32 v204, v199
	v_max_f32_e32 v199, v204, v199
	v_max_f32_e32 v204, 0, v199
	v_exp_f32_e64 v199, -v204
	v_add_f32_e32 v195, v195, v204
	v_pk_add_f32 v[96:97], v[96:97], v[204:205] op_sel_hi:[1,0] neg_lo:[0,1] neg_hi:[0,1]
	v_pk_add_f32 v[98:99], v[98:99], v[204:205] op_sel_hi:[1,0] neg_lo:[0,1] neg_hi:[0,1]
	v_pk_add_f32 v[100:101], v[100:101], v[204:205] op_sel_hi:[1,0] neg_lo:[0,1] neg_hi:[0,1]
	v_pk_add_f32 v[102:103], v[102:103], v[204:205] op_sel_hi:[1,0] neg_lo:[0,1] neg_hi:[0,1]
	v_pk_add_f32 v[104:105], v[104:105], v[204:205] op_sel_hi:[1,0] neg_lo:[0,1] neg_hi:[0,1]
	v_pk_add_f32 v[106:107], v[106:107], v[204:205] op_sel_hi:[1,0] neg_lo:[0,1] neg_hi:[0,1]
	v_pk_add_f32 v[108:109], v[108:109], v[204:205] op_sel_hi:[1,0] neg_lo:[0,1] neg_hi:[0,1]
	v_pk_add_f32 v[110:111], v[110:111], v[204:205] op_sel_hi:[1,0] neg_lo:[0,1] neg_hi:[0,1]
	v_sub_f32_e32 v79, v79, v204
	v_sub_f32_e32 v78, v78, v204
	v_sub_f32_e32 v77, v77, v204
	v_sub_f32_e32 v76, v76, v204
	v_sub_f32_e32 v75, v75, v204
	v_sub_f32_e32 v74, v74, v204
	v_sub_f32_e32 v73, v73, v204
	v_sub_f32_e32 v72, v72, v204
	v_sub_f32_e32 v71, v71, v204
	v_sub_f32_e32 v70, v70, v204
	v_sub_f32_e32 v69, v69, v204
	v_sub_f32_e32 v68, v68, v204
	v_sub_f32_e32 v67, v67, v204
	v_sub_f32_e32 v66, v66, v204
	v_sub_f32_e32 v65, v65, v204
	v_sub_f32_e32 v64, v64, v204
	v_cmp_gt_f32_e64 s[100:101], 1.0, v199
	s_branch .LBB0_432
